# M1: bank-conflict swizzle of the partial column-sum tile (dnp) writes and its reduction reads
# speedup vs baseline: 1.0137x; 1.0013x over previous
.LBB0_374:
	s_or_b64 exec, exec, s[2:3]
	v_lshlrev_b32_e32 v60, 3, v2
	s_and_b32 s0, s20, 0x180
	v_and_b32_e32 v85, 0x78, v60
	s_lshl_b32 s0, s0, 2
	s_add_i32 s0, s0, 0
	v_lshlrev_b32_e32 v114, 2, v85
	v_add_u32_e32 v60, s0, v114
	v_add_u32_e32 v110, 0x10800, v60
	ds_read_b128 v[86:89], v110
	ds_read_b128 v[60:63], v110 offset:16
	ds_read_b128 v[90:93], v110 offset:4096
	ds_read_b128 v[94:97], v110 offset:8192
	ds_read_b128 v[98:101], v110 offset:12288
	v_lshlrev_b32_e32 v117, 16, v41
	v_and_b32_e32 v41, 0xffff0000, v41
	v_lshlrev_b32_e32 v115, 16, v57
	v_and_b32_e32 v57, 0xffff0000, v57
	s_waitcnt lgkmcnt(2)
	v_mul_f32_e32 v128, v93, v41
	v_lshlrev_b32_e32 v119, 16, v49
	v_and_b32_e32 v49, 0xffff0000, v49
	v_fmac_f32_e32 v128, v89, v57
	v_lshlrev_b32_e32 v121, 16, v53
	v_and_b32_e32 v53, 0xffff0000, v53
	s_waitcnt lgkmcnt(1)
	v_fmac_f32_e32 v128, v97, v49
	s_waitcnt lgkmcnt(0)
	v_fmac_f32_e32 v128, v101, v53
	v_mul_f32_e32 v57, 0xbfb8aa3b, v128
	v_exp_f32_e32 v57, v57
	v_lshlrev_b32_e32 v116, 16, v40
	v_and_b32_e32 v40, 0xffff0000, v40
	v_lshlrev_b32_e32 v118, 16, v48
	v_lshlrev_b32_e32 v106, 16, v56
	v_and_b32_e32 v56, 0xffff0000, v56
	v_mul_f32_e32 v123, v90, v116
	v_mul_f32_e32 v126, v91, v40
	v_add_f32_e32 v57, 1.0, v57
	v_mul_f32_e32 v90, v90, v118
	v_and_b32_e32 v48, 0xffff0000, v48
	v_lshlrev_b32_e32 v120, 16, v52
	v_fmac_f32_e32 v126, v87, v56
	v_rcp_f32_e32 v57, v57
	v_fmac_f32_e32 v90, v86, v116
	v_lshlrev_b32_e32 v122, 16, v44
	v_fmac_f32_e32 v126, v95, v48
	v_fmac_f32_e32 v90, v94, v120
	v_mul_f32_e32 v48, v91, v48
	v_and_b32_e32 v52, 0xffff0000, v52
	v_fmac_f32_e32 v90, v98, v122
	v_fmac_f32_e32 v48, v87, v40
	v_fmac_f32_e32 v123, v86, v106
	v_and_b32_e32 v44, 0xffff0000, v44
	v_mul_f32_e32 v86, 0xbfb8aa3b, v90
	v_fmac_f32_e32 v48, v95, v52
	v_exp_f32_e32 v86, v86
	v_fmac_f32_e32 v48, v99, v44
	v_mul_f32_e32 v44, v128, v57
	v_mul_f32_e32 v57, v92, v119
	v_fmac_f32_e32 v57, v88, v117
	v_lshlrev_b32_e32 v125, 16, v45
	v_fmac_f32_e32 v57, v96, v121
	v_fmac_f32_e32 v57, v100, v125
	v_fmac_f32_e32 v126, v99, v52
	v_add_f32_e32 v52, 1.0, v86
	v_mul_f32_e32 v86, 0xbfb8aa3b, v57
	v_exp_f32_e32 v86, v86
	v_mul_f32_e32 v49, v93, v49
	v_fmac_f32_e32 v49, v89, v41
	v_and_b32_e32 v45, 0xffff0000, v45
	v_fmac_f32_e32 v49, v97, v53
	v_fmac_f32_e32 v49, v101, v45
	v_add_f32_e32 v45, 1.0, v86
	ds_read_b128 v[102:105], v110 offset:4112
	ds_read_b128 v[106:109], v110 offset:8208
	v_rcp_f32_e32 v45, v45
	v_mul_f32_e32 v40, 0xbfb8aa3b, v48
	v_mul_f32_e32 v41, 0xbfb8aa3b, v49
	v_exp_f32_e32 v40, v40
	v_exp_f32_e32 v41, v41
	ds_read_b128 v[110:113], v110 offset:12304
	v_mul_f32_e32 v45, v57, v45
	v_lshlrev_b32_e32 v53, 16, v59
	v_and_b32_e32 v57, 0xffff0000, v59
	v_lshlrev_b32_e32 v59, 16, v43
	v_and_b32_e32 v43, 0xffff0000, v43
	s_waitcnt lgkmcnt(2)
	v_mul_f32_e32 v95, v105, v43
	v_add_f32_e32 v40, 1.0, v40
	v_add_f32_e32 v41, 1.0, v41
	v_lshlrev_b32_e32 v87, 16, v51
	v_and_b32_e32 v51, 0xffff0000, v51
	v_fmac_f32_e32 v95, v63, v57
	v_rcp_f32_e32 v40, v40
	v_rcp_f32_e32 v41, v41
	v_lshlrev_b32_e32 v89, 16, v55
	v_and_b32_e32 v55, 0xffff0000, v55
	s_waitcnt lgkmcnt(1)
	v_fmac_f32_e32 v95, v109, v51
	s_waitcnt lgkmcnt(0)
	v_fmac_f32_e32 v95, v113, v55
	v_mul_f32_e32 v57, 0xbfb8aa3b, v95
	v_exp_f32_e32 v57, v57
	v_mul_f32_e32 v40, v48, v40
	v_mul_f32_e32 v41, v49, v41
	v_lshlrev_b32_e32 v48, 16, v58
	v_and_b32_e32 v49, 0xffff0000, v58
	v_lshlrev_b32_e32 v58, 16, v42
	v_rcp_f32_e32 v52, v52
	v_mul_f32_e32 v91, v102, v58
	v_and_b32_e32 v42, 0xffff0000, v42
	v_lshlrev_b32_e32 v86, 16, v50
	v_fmac_f32_e32 v91, v60, v48
	v_mul_f32_e32 v127, v92, v117
	v_fmac_f32_e32 v91, v106, v86
	v_mul_f32_e32 v93, v103, v42
	v_add_f32_e32 v57, 1.0, v57
	v_mul_f32_e32 v86, v102, v86
	v_fmac_f32_e32 v127, v88, v115
	v_and_b32_e32 v50, 0xffff0000, v50
	v_lshlrev_b32_e32 v88, 16, v54
	v_fmac_f32_e32 v93, v61, v49
	v_rcp_f32_e32 v57, v57
	v_fmac_f32_e32 v86, v60, v58
	v_mul_f32_e32 v52, v90, v52
	v_lshlrev_b32_e32 v90, 16, v46
	v_fmac_f32_e32 v93, v107, v50
	v_fmac_f32_e32 v86, v106, v88
	v_mul_f32_e32 v50, v103, v50
	v_and_b32_e32 v54, 0xffff0000, v54
	v_fmac_f32_e32 v86, v110, v90
	v_fmac_f32_e32 v50, v61, v42
	v_and_b32_e32 v46, 0xffff0000, v46
	v_mul_f32_e32 v58, 0xbfb8aa3b, v86
	v_fmac_f32_e32 v50, v107, v54
	v_exp_f32_e32 v58, v58
	v_fmac_f32_e32 v50, v111, v46
	v_mul_f32_e32 v46, v95, v57
	v_mul_f32_e32 v57, v104, v87
	v_fmac_f32_e32 v57, v62, v59
	v_fmac_f32_e32 v123, v94, v118
	v_lshlrev_b32_e32 v92, 16, v47
	v_fmac_f32_e32 v57, v108, v89
	v_fmac_f32_e32 v123, v98, v120
	v_fmac_f32_e32 v57, v112, v92
	v_mul_f32_e32 v124, 0xbfb8aa3b, v123
	v_fmac_f32_e32 v93, v111, v54
	v_add_f32_e32 v54, 1.0, v58
	v_mul_f32_e32 v58, 0xbfb8aa3b, v57
	v_exp_f32_e32 v124, v124
	v_exp_f32_e32 v58, v58
	v_mul_f32_e32 v42, 0xbfb8aa3b, v50
	v_mul_f32_e32 v51, v105, v51
	v_ashrrev_i32_e32 v84, 4, v2
	v_mul_f32_e32 v56, 0xbfb8aa3b, v126
	v_mul_f32_e32 v94, v104, v59
	v_exp_f32_e32 v42, v42
	v_fmac_f32_e32 v51, v63, v43
	v_exp_f32_e32 v56, v56
	v_fmac_f32_e32 v127, v96, v119
	v_and_b32_e32 v47, 0xffff0000, v47
	v_fmac_f32_e32 v94, v62, v53
	v_fmac_f32_e32 v51, v109, v55
	v_lshl_add_u32 v62, v84, 3, 0
	v_add_f32_e32 v124, 1.0, v124
	v_fmac_f32_e32 v127, v100, v121
	v_fmac_f32_e32 v51, v113, v47
	v_add_f32_e32 v47, 1.0, v58
	v_lshlrev_b32_e32 v58, 16, v32
	v_and_b32_e32 v59, 0xffff0000, v32
	v_lshlrev_b32_e32 v60, 16, v33
	v_and_b32_e32 v61, 0xffff0000, v33
	s_barrier
	ds_read_b64 v[32:33], v62 offset:36864
	v_mul_f32_e32 v115, 0xbfb8aa3b, v127
	v_rcp_f32_e32 v124, v124
	v_exp_f32_e32 v115, v115
	v_add_f32_e32 v42, 1.0, v42
	v_add_f32_e32 v56, 1.0, v56
	v_rcp_f32_e32 v42, v42
	v_rcp_f32_e32 v56, v56
	v_mul_f32_e32 v43, 0xbfb8aa3b, v51
	v_mul_f32_e32 v123, v123, v124
	v_fmac_f32_e32 v94, v108, v87
	v_exp_f32_e32 v43, v43
	s_waitcnt lgkmcnt(0)
	v_mul_f32_e32 v32, 0x3db504f3, v32
	v_mul_f32_e32 v33, 0x3db504f3, v33
	v_lshlrev_b32_e32 v87, 2, v84
	v_add_f32_e32 v115, 1.0, v115
	v_fmac_f32_e32 v91, v110, v88
	v_fmac_f32_e32 v94, v112, v89
	v_sub_u32_e32 v62, v62, v87
	v_lshlrev_b32_e32 v87, 9, v84
	v_mul_f32_e32 v88, v123, v32
	v_mul_f32_e32 v52, v52, v33
	v_mul_u32_u24_e32 v89, 0x48, v85
	v_rcp_f32_e32 v115, v115
	v_mul_f32_e32 v48, 0xbfb8aa3b, v91
	v_mul_f32_e32 v42, v50, v42
	v_lshlrev_b32_e32 v50, 16, v36
	v_add3_u32 v87, 0, v114, v87
	v_bfe_u32 v132, v85, 5, 2
	v_lshl_add_u32 v133, v132, 2, v87
	v_xor_b32_e32 v134, 1, v132
	v_lshl_add_u32 v134, v134, 2, v87
	v_xor_b32_e32 v135, 2, v132
	v_lshl_add_u32 v135, v135, 2, v87
	v_xor_b32_e32 v136, 3, v132
	v_lshl_add_u32 v136, v136, 2, v87
	v_cvt_pk_bf16_f32 v88, v88, v52
	v_lshrrev_b32_e32 v130, 2, v84
	v_and_b32_e32 v131, 7, v2
	v_xor_b32_e32 v130, v130, v131
	v_and_b32_e32 v131, 3, v84
	v_lshlrev_b32_e32 v131, 2, v131
	v_lshl_or_b32 v130, v130, 4, v131
	v_lshl_add_u32 v62, v89, 1, v130
	v_fmac_f32_e32 v52, v123, v32
	v_mul_f32_e32 v56, v126, v56
	v_exp_f32_e32 v48, v48
	ds_write_b32 v62, v88
	ds_write_b32 v133, v52 offset:37120
	v_cvt_pk_bf16_f32 v50, v50, v58
	v_add_f32_e32 v43, 1.0, v43
	ds_write_b32 v62, v50 offset:18432
	v_mul_f32_e32 v50, v56, v32
	v_mul_f32_e32 v40, v40, v33
	v_mul_f32_e32 v49, 0xbfb8aa3b, v93
	v_rcp_f32_e32 v43, v43
	v_and_b32_e32 v36, 0xffff0000, v36
	v_cvt_pk_bf16_f32 v50, v50, v40
	v_fmac_f32_e32 v40, v56, v32
	v_mul_f32_e32 v115, v127, v115
	v_exp_f32_e32 v49, v49
	ds_write_b32 v62, v50 offset:144
	ds_write_b32 v134, v40 offset:37120
	v_cvt_pk_bf16_f32 v36, v36, v59
	v_add_f32_e32 v48, 1.0, v48
	ds_write_b32 v62, v36 offset:18576
	v_mul_f32_e32 v36, v115, v32
	v_mul_f32_e32 v40, v45, v33
	v_mul_f32_e32 v53, 0xbfb8aa3b, v94
	v_rcp_f32_e32 v48, v48
	v_rcp_f32_e32 v54, v54
	v_cvt_pk_bf16_f32 v36, v36, v40
	v_fmac_f32_e32 v40, v115, v32
	v_exp_f32_e32 v53, v53
	v_mul_f32_e32 v43, v51, v43
	v_lshlrev_b32_e32 v51, 16, v37
	ds_write_b32 v62, v36 offset:288
	ds_write_b32 v135, v40 offset:37120
	v_cvt_pk_bf16_f32 v36, v51, v60
	v_add_f32_e32 v49, 1.0, v49
	ds_write_b32 v62, v36 offset:18720
	v_mul_f32_e32 v36, v44, v32
	v_mul_f32_e32 v40, v41, v33
	v_rcp_f32_e32 v49, v49
	v_cvt_pk_bf16_f32 v36, v36, v40
	v_fmac_f32_e32 v40, v44, v32
	v_mul_f32_e32 v48, v91, v48
	v_mul_f32_e32 v54, v86, v54
	v_and_b32_e32 v37, 0xffff0000, v37
	ds_write_b32 v62, v36 offset:432
	ds_write_b32 v136, v40 offset:37120
	v_cvt_pk_bf16_f32 v36, v37, v61
	v_add_f32_e32 v53, 1.0, v53
	ds_write_b32 v62, v36 offset:18864
	v_mul_f32_e32 v36, v32, v48
	v_mul_f32_e32 v37, v33, v54
	v_rcp_f32_e32 v53, v53
	v_rcp_f32_e32 v47, v47
	v_cvt_pk_bf16_f32 v36, v36, v37
	v_fmac_f32_e32 v37, v32, v48
	v_mul_f32_e32 v49, v93, v49
	v_lshlrev_b32_e32 v55, 16, v38
	v_lshlrev_b32_e32 v63, 16, v34
	ds_write_b32 v62, v36 offset:576
	ds_write_b32 v133, v37 offset:37136
	v_cvt_pk_bf16_f32 v36, v55, v63
	ds_write_b32 v62, v36 offset:19008
	v_mul_f32_e32 v36, v32, v49
	v_mul_f32_e32 v37, v33, v42
	v_and_b32_e32 v34, 0xffff0000, v34
	v_cvt_pk_bf16_f32 v36, v36, v37
	v_fmac_f32_e32 v37, v32, v49
	v_mul_f32_e32 v53, v94, v53
	v_mul_f32_e32 v47, v57, v47
	v_and_b32_e32 v38, 0xffff0000, v38
	ds_write_b32 v62, v36 offset:720
	ds_write_b32 v134, v37 offset:37136
	v_cvt_pk_bf16_f32 v34, v38, v34
	ds_write_b32 v62, v34 offset:19152
	v_mul_f32_e32 v34, v32, v53
	v_mul_f32_e32 v36, v33, v47
	v_cvt_pk_bf16_f32 v34, v34, v36
	v_fmac_f32_e32 v36, v32, v53
	v_lshlrev_b32_e32 v57, 16, v39
	v_lshlrev_b32_e32 v86, 16, v35
	ds_write_b32 v62, v34 offset:864
	ds_write_b32 v135, v36 offset:37136
	v_cvt_pk_bf16_f32 v34, v57, v86
	ds_write_b32 v62, v34 offset:19296
	v_mul_f32_e32 v34, v32, v46
	v_mul_f32_e32 v33, v33, v43
	v_cvt_pk_bf16_f32 v34, v34, v33
	v_fmac_f32_e32 v33, v32, v46
	v_cmp_lt_i32_e64 s[0:1], s35, v2
	v_and_b32_e32 v39, 0xffff0000, v39
	v_and_b32_e32 v35, 0xffff0000, v35
	ds_write_b32 v62, v34 offset:1008
	ds_write_b32 v136, v33 offset:37136
	v_cvt_pk_bf16_f32 v32, v39, v35
	ds_write_b32 v62, v32 offset:19440
	s_waitcnt lgkmcnt(0)
	s_barrier
	s_and_saveexec_b64 s[28:29], s[0:1]
	s_xor_b64 s[0:1], exec, s[28:29]
	s_bfe_i64 s[2:3], s[22:23], 0x200000
	s_or_saveexec_b64 s[0:1], s[0:1]
	v_mov_b64_e32 v[32:33], s[2:3]
	s_xor_b64 exec, exec, s[0:1]
	s_cbranch_execz .LBB0_360
	v_bfe_u32 v138, v2, 5, 2
	v_xor_b32_e32 v138, v138, v2
	v_lshlrev_b32_e32 v138, 2, v138
	ds_read2st64_b32 v[32:33], v138 offset0:145 offset1:147
	ds_read2st64_b32 v[34:35], v138 offset0:149 offset1:151
	ds_read2st64_b32 v[36:37], v138 offset0:153 offset1:155
	ds_read2st64_b32 v[38:39], v138 offset0:157 offset1:159
	ds_read2st64_b32 v[40:41], v138 offset0:161 offset1:163
	s_waitcnt lgkmcnt(4)
	v_add_f32_e32 v32, 0, v32
	v_add_f32_e32 v32, v32, v33
	s_waitcnt lgkmcnt(3)
	v_add_f32_e32 v32, v32, v34
	v_add_f32_e32 v32, v32, v35
	s_waitcnt lgkmcnt(2)
	v_add_f32_e32 v32, v32, v36
	v_add_f32_e32 v32, v32, v37
	s_waitcnt lgkmcnt(1)
	v_add_f32_e32 v34, v32, v38
	ds_read2st64_b32 v[32:33], v138 offset0:165 offset1:167
	v_add_f32_e32 v34, v34, v39
	s_waitcnt lgkmcnt(1)
	v_add_f32_e32 v36, v34, v40
	ds_read2st64_b32 v[34:35], v138 offset0:169 offset1:171
	v_add_f32_e32 v36, v36, v41
	s_waitcnt lgkmcnt(1)
	v_add_f32_e32 v32, v36, v32
	ds_read2st64_b32 v[36:37], v138 offset0:173 offset1:175
	v_add_f32_e32 v32, v32, v33
	s_waitcnt lgkmcnt(1)
	v_add_f32_e32 v34, v32, v34
	ds_read2st64_b32 v[32:33], v138 offset0:177 offset1:179
	v_add_f32_e32 v34, v34, v35
	s_waitcnt lgkmcnt(1)
	v_add_f32_e32 v36, v34, v36
	ds_read2st64_b32 v[34:35], v138 offset0:181 offset1:183
	v_add_f32_e32 v36, v36, v37
	s_waitcnt lgkmcnt(1)
	v_add_f32_e32 v32, v36, v32
	ds_read2st64_b32 v[36:37], v138 offset0:185 offset1:187
	v_add_f32_e32 v32, v32, v33
	s_waitcnt lgkmcnt(1)
	v_add_f32_e32 v34, v32, v34
	ds_read2st64_b32 v[32:33], v138 offset0:189 offset1:191
	v_add_f32_e32 v34, v34, v35
	s_waitcnt lgkmcnt(1)
	v_add_f32_e32 v36, v34, v36
	ds_read2st64_b32 v[34:35], v138 offset0:193 offset1:195
	v_add_f32_e32 v36, v36, v37
	s_waitcnt lgkmcnt(1)
	v_add_f32_e32 v32, v36, v32
	v_add_f32_e32 v36, v32, v33
	ds_read2st64_b32 v[32:33], v138 offset0:197 offset1:199
	s_waitcnt lgkmcnt(1)
	v_add_f32_e32 v34, v36, v34
	ds_read2st64_b32 v[36:37], v138 offset0:201 offset1:203
	v_add_f32_e32 v38, v34, v35
	ds_read2st64_b32 v[34:35], v138 offset0:205 offset1:207
	s_waitcnt lgkmcnt(2)
	v_add_f32_e32 v3, v38, v32
	v_add_f32_e32 v3, v3, v33
	s_waitcnt lgkmcnt(1)
	v_add_f32_e32 v3, v3, v36
	v_add_f32_e32 v3, v3, v37
	s_waitcnt lgkmcnt(0)
	v_add_f32_e32 v3, v3, v34
	v_add_f32_e32 v34, v3, v35
	v_ashrrev_i32_e32 v3, 31, v2
	v_lshl_add_u64 v[32:33], v[2:3], 2, s[24:25]
	global_store_dword v[32:33], v34, off
	v_mov_b64_e32 v[32:33], s[22:23]
	s_branch .LBB0_360
